# phase 3 prompt in-proj GEMM: XCD-balanced mapping (max 5 tiles per block) on top of DeltaNet read hoisting
# speedup vs baseline: 1.0001x; 1.0001x over previous
.LBB0_409:
	s_and_b32 s15, s84, 7
	s_lshr_b32 s16, s16, 3
	s_mov_b32 s18, 64
	s_mov_b32 s17, 8

.LBB0_412:
	s_ashr_i32 s0, s22, 6
	s_add_i32 s1, s84, 0xffffff80
	s_lshr_b32 s1, s1, 3
	s_mul_i32 s4, s0, 48
	s_add_i32 s1, s1, s4
	s_mov_b32 s6, 2
	s_cmp_gt_i32 s1, 227
	s_cbranch_scc1 .LBB0_499
	s_and_b32 s4, s84, 7
	s_mul_i32 s4, s4, 228
	s_add_i32 s1, s1, s4
	s_cmp_gt_i32 s1, 455
	s_cselect_b32 s4, 1, 0
	s_cmp_gt_i32 s1, 911
	s_cselect_b32 s5, 1, 0
	s_add_i32 s4, s4, s5
	s_cmp_gt_i32 s1, 1367
	s_cselect_b32 s5, 1, 0
	s_add_i32 s4, s4, s5
	s_mul_i32 s5, s4, 456
	s_sub_i32 s1, s1, s5
	s_lshr_b32 s5, s1, 3
	s_and_b32 s1, s1, 7
	s_lshl_b32 s4, s4, 3
	s_lshr_b32 s7, s5, 3
	s_add_i32 s4, s4, s7
	s_and_b32 s5, s5, 7
	s_lshl_b32 s5, s5, 3
	s_or_b32 s5, s5, s1
	s_lshl_b32 s0, s0, 6
	s_or_b32 s22, s0, s5
	s_mov_b32 s16, s5
	s_mov_b32 s0, s4
	s_ashr_i32 s1, s0, 31
	s_lshr_b32 s1, s1, 29
	s_add_i32 s5, s0, s1
	s_and_b32 s1, s5, -8
	s_and_b32 s4, s22, 7
	s_or_b32 s4, s1, s4
	s_sub_i32 s1, s0, s1
	s_lshl_b32 s6, s1, 3
	s_bfe_u32 s1, s22, 0x30003
	s_or_b32 s7, s6, s1
	s_cmp_gt_i32 s4, 31
	s_cselect_b64 s[10:11], -1, 0
	s_cmp_gt_i32 s7, 56
	s_cselect_b64 s[12:13], -1, 0
	s_or_b64 s[10:11], s[10:11], s[12:13]
	s_mov_b32 s6, 4
	s_and_b64 vcc, exec, s[10:11]
	s_cbranch_vccnz .LBB0_499
	s_ashr_i32 s23, s5, 3
	s_and_b32 s5, s16, 7
	s_lshl_b32 s4, s4, 8
	s_lshl_b32 s24, s5, 8
	s_ashr_i32 s5, s4, 31
	s_lshl_b64 s[12:13], s[4:5], 11
	v_lshl_add_u64 v[0:1], v[186:187], 0, s[12:13]
	v_add_co_u32_e32 v2, vcc, 0x10000, v0
	s_lshl_b32 s10, s7, 7
	s_nop 0
	v_addc_co_u32_e32 v3, vcc, 0, v1, vcc
	s_nop 0
	v_readfirstlane_b32 s98, v0
	v_readfirstlane_b32 s99, v1
	v_add_co_u32_e32 v2, vcc, 0x20000, v0
	s_ashr_i32 s11, s10, 31
	s_nop 0
	v_addc_co_u32_e32 v3, vcc, 0, v1, vcc
	v_add_co_u32_e32 v4, vcc, 0x30000, v0
	s_lshl_b64 s[6:7], s[10:11], 11
	s_nop 0
	v_addc_co_u32_e32 v5, vcc, 0, v1, vcc
	v_add_co_u32_e32 v2, vcc, 0x40000, v0
	s_mov_b32 s5, 0x10000
	s_nop 0
	v_addc_co_u32_e32 v3, vcc, 0, v1, vcc
	v_add_co_u32_e32 v4, vcc, 0x50000, v0
	s_lshl_b32 s0, s0, 3
	s_nop 0
	v_addc_co_u32_e32 v5, vcc, 0, v1, vcc
	v_add_co_u32_e32 v2, vcc, 0x60000, v0
	s_or_b32 s0, s0, s1
	s_nop 0
	v_addc_co_u32_e32 v3, vcc, 0, v1, vcc
	v_add_co_u32_e32 v0, vcc, 0x70000, v0
	s_lshl_b32 s1, s23, 6
	s_nop 0
	v_addc_co_u32_e32 v1, vcc, 0, v1, vcc
	v_lshl_add_u64 v[0:1], v[188:189], 0, s[6:7]
	v_add_co_u32_e32 v2, vcc, s5, v0
	s_mov_b32 s5, 0x20000
	s_nop 0
	v_addc_co_u32_e32 v3, vcc, 0, v1, vcc
	s_nop 0
	v_readfirstlane_b32 s100, v0
	v_readfirstlane_b32 s101, v1
	v_add_co_u32_e32 v2, vcc, s5, v0
	s_mov_b32 s5, 0x30000
	s_nop 0
	v_addc_co_u32_e32 v3, vcc, 0, v1, vcc
	v_add_co_u32_e32 v0, vcc, s5, v0
	s_lshl_b32 s5, s23, 11
	s_nop 0
	v_addc_co_u32_e32 v1, vcc, 0, v1, vcc
	s_sub_i32 s0, s0, s1
	s_or_b32 s6, s5, s24
	s_lshl_b32 s0, s0, 7
	s_ashr_i32 s7, s6, 31
	s_ashr_i32 s1, s0, 31
	s_lshl_b64 s[6:7], s[6:7], 11
	s_lshl_b64 s[0:1], s[0:1], 11
	v_mov_b32_e32 v124, 0
	v_lshl_add_u64 v[192:193], v[190:191], 0, s[6:7]
	v_lshl_add_u64 v[194:195], v[190:191], 0, s[0:1]
	s_mov_b64 s[0:1], 0
	v_mov_b32_e32 v125, v124
	v_mov_b32_e32 v126, v124
	v_mov_b32_e32 v127, v124
	v_mov_b32_e32 v80, v124
	v_mov_b32_e32 v81, v124
	v_mov_b32_e32 v82, v124
	v_mov_b32_e32 v83, v124
	v_mov_b32_e32 v88, v124
	v_mov_b32_e32 v89, v124
	v_mov_b32_e32 v90, v124
	v_mov_b32_e32 v91, v124
	v_mov_b32_e32 v92, v124
	v_mov_b32_e32 v93, v124
	v_mov_b32_e32 v94, v124
	v_mov_b32_e32 v95, v124
	v_mov_b32_e32 v100, v124
	v_mov_b32_e32 v101, v124
	v_mov_b32_e32 v102, v124
	v_mov_b32_e32 v103, v124
	v_mov_b32_e32 v104, v124
	v_mov_b32_e32 v105, v124
	v_mov_b32_e32 v106, v124
	v_mov_b32_e32 v107, v124
	v_mov_b32_e32 v48, v124
	v_mov_b32_e32 v49, v124
	v_mov_b32_e32 v50, v124
	v_mov_b32_e32 v51, v124
	v_mov_b32_e32 v40, v124
	v_mov_b32_e32 v41, v124
	v_mov_b32_e32 v42, v124
	v_mov_b32_e32 v43, v124
	v_mov_b32_e32 v52, v124
	v_mov_b32_e32 v53, v124
	v_mov_b32_e32 v54, v124
	v_mov_b32_e32 v55, v124
	v_mov_b32_e32 v44, v124
	v_mov_b32_e32 v45, v124
	v_mov_b32_e32 v46, v124
	v_mov_b32_e32 v47, v124
	v_mov_b32_e32 v32, v124
	v_mov_b32_e32 v33, v124
	v_mov_b32_e32 v34, v124
	v_mov_b32_e32 v35, v124
	v_mov_b32_e32 v12, v124
	v_mov_b32_e32 v13, v124
	v_mov_b32_e32 v14, v124
	v_mov_b32_e32 v15, v124
	v_mov_b32_e32 v36, v124
	v_mov_b32_e32 v37, v124
	v_mov_b32_e32 v38, v124
	v_mov_b32_e32 v39, v124
	v_mov_b32_e32 v16, v124
	v_mov_b32_e32 v17, v124
	v_mov_b32_e32 v18, v124
	v_mov_b32_e32 v19, v124
	v_mov_b32_e32 v8, v124
	v_mov_b32_e32 v9, v124
	v_mov_b32_e32 v10, v124
	v_mov_b32_e32 v11, v124
	v_mov_b32_e32 v0, v124
	v_mov_b32_e32 v1, v124
	v_mov_b32_e32 v2, v124
	v_mov_b32_e32 v3, v124
	v_mov_b32_e32 v20, v124
	v_mov_b32_e32 v21, v124
	v_mov_b32_e32 v22, v124
	v_mov_b32_e32 v23, v124
	v_mov_b32_e32 v24, v124
	v_mov_b32_e32 v25, v124
	v_mov_b32_e32 v26, v124
	v_mov_b32_e32 v27, v124
	v_mov_b32_e32 v4, v124
	v_mov_b32_e32 v5, v124
	v_mov_b32_e32 v6, v124
	v_mov_b32_e32 v7, v124
	v_mov_b32_e32 v28, v124
	v_mov_b32_e32 v29, v124
	v_mov_b32_e32 v30, v124
	v_mov_b32_e32 v31, v124
	v_mov_b32_e32 v56, v124
	v_mov_b32_e32 v57, v124
	v_mov_b32_e32 v58, v124
	v_mov_b32_e32 v59, v124
	v_mov_b32_e32 v60, v124
	v_mov_b32_e32 v61, v124
	v_mov_b32_e32 v62, v124
	v_mov_b32_e32 v63, v124
	v_mov_b32_e32 v64, v124
	v_mov_b32_e32 v65, v124
	v_mov_b32_e32 v66, v124
	v_mov_b32_e32 v67, v124
	v_mov_b32_e32 v68, v124
	v_mov_b32_e32 v69, v124
	v_mov_b32_e32 v70, v124
	v_mov_b32_e32 v71, v124
	v_mov_b32_e32 v72, v124
	v_mov_b32_e32 v73, v124
	v_mov_b32_e32 v74, v124
	v_mov_b32_e32 v75, v124
	v_mov_b32_e32 v76, v124
	v_mov_b32_e32 v77, v124
	v_mov_b32_e32 v78, v124
	v_mov_b32_e32 v79, v124
	v_mov_b32_e32 v84, v124
	v_mov_b32_e32 v85, v124
	v_mov_b32_e32 v86, v124
	v_mov_b32_e32 v87, v124
	v_mov_b32_e32 v96, v124
	v_mov_b32_e32 v97, v124
	v_mov_b32_e32 v98, v124
	v_mov_b32_e32 v99, v124
	v_mov_b32_e32 v108, v124
	v_mov_b32_e32 v109, v124
	v_mov_b32_e32 v110, v124
	v_mov_b32_e32 v111, v124
	v_mov_b32_e32 v112, v124
	v_mov_b32_e32 v113, v124
	v_mov_b32_e32 v114, v124
	v_mov_b32_e32 v115, v124
	v_mov_b32_e32 v116, v124
	v_mov_b32_e32 v117, v124
	v_mov_b32_e32 v118, v124
	v_mov_b32_e32 v119, v124
	v_mov_b32_e32 v120, v124
	v_mov_b32_e32 v121, v124
	v_mov_b32_e32 v122, v124
	v_mov_b32_e32 v123, v124
	v_mov_b32_e32 v194, 0
	ds_read_b64 v[192:193], v194
	v_and_b32_e32 v195, 63, v196
	v_lshrrev_b32_e32 v242, 3, v195
	v_and_b32_e32 v239, 7, v195
	v_xor_b32_e32 v239, v239, v242
	v_lshlrev_b32_e32 v239, 4, v239
	v_mul_u32_u24_e32 v242, 2048, v242
	v_add_u32_e32 v252, v242, v239
	v_add_u32_e32 v251, 65536, v252
	v_add_u32_e32 v248, 131072, v252
	v_add_u32_e32 v249, 196608, v252
	v_add_u32_e32 v250, 262144, v252
	v_add_u32_e32 v247, 327680, v252
	v_add_u32_e32 v244, 393216, v252
	v_add_u32_e32 v245, 458752, v252
	v_lshrrev_b32_e32 v242, 6, v196
	v_lshrrev_b32_e32 v239, 1, v242
	v_and_b32_e32 v242, 1, v242
	v_and_b32_e32 v236, 15, v195
	v_lshrrev_b32_e32 v237, 4, v195
	v_and_b32_e32 v238, 7, v236
	v_xor_b32_e32 v237, v237, v238
	v_lshlrev_b32_e32 v237, 4, v237
	v_lshlrev_b32_e32 v239, 7, v239
	v_add_u32_e32 v239, v239, v236
	v_lshl_add_u32 v246, v239, 7, v237
	v_xor_b32_e32 v243, 64, v246
	v_lshlrev_b32_e32 v242, 6, v242
	v_add_u32_e32 v242, v242, v236
	v_lshl_add_u32 v240, v242, 7, v237
	v_add_u32_e32 v240, 65536, v240
	v_xor_b32_e32 v241, 64, v240
	v_lshrrev_b32_e32 v242, 6, v196
	v_lshlrev_b32_e32 v242, 10, v242
	s_nop 0
	v_readfirstlane_b32 s0, v242
	s_waitcnt lgkmcnt(0)
	s_barrier
	s_add_u32 m0, s0, 0
	s_nop 0
	global_load_lds_dwordx4 v252, s[98:99]
	s_add_u32 m0, s0, 4096
	s_nop 0
	global_load_lds_dwordx4 v251, s[98:99]
	s_add_u32 m0, s0, 8192
	s_nop 0
	global_load_lds_dwordx4 v248, s[98:99]
	s_add_u32 m0, s0, 12288
	s_nop 0
	global_load_lds_dwordx4 v249, s[98:99]
	s_add_u32 m0, s0, 16384
	s_nop 0
	global_load_lds_dwordx4 v250, s[98:99]
	s_add_u32 m0, s0, 20480
	s_nop 0
	global_load_lds_dwordx4 v247, s[98:99]
	s_add_u32 m0, s0, 24576
	s_nop 0
	global_load_lds_dwordx4 v244, s[98:99]
	s_add_u32 m0, s0, 28672
	s_nop 0
	global_load_lds_dwordx4 v245, s[98:99]
	s_add_u32 m0, s0, 65536
	s_nop 0
	global_load_lds_dwordx4 v252, s[100:101]
	s_add_u32 m0, s0, 69632
	s_nop 0
	global_load_lds_dwordx4 v251, s[100:101]
	s_add_u32 m0, s0, 73728
	s_nop 0
	global_load_lds_dwordx4 v248, s[100:101]
	s_add_u32 m0, s0, 77824
	s_nop 0
	global_load_lds_dwordx4 v249, s[100:101]
	s_add_u32 s98, s98, 0x80
	s_addc_u32 s99, s99, 0
	s_add_u32 s100, s100, 0x80
	s_addc_u32 s101, s101, 0
	s_mov_b32 s1, 7
